# as before, and the last k-loop iteration no longer prefetches fragments the peeled k-tile re-reads
# baseline (speedup 1.0000x reference)
; #define MFMA16(a, b, c) __builtin_amdgcn_mfma_f32_16x16x32_bf16((a), (b), (c), 0, 0, 0)
; template <class Epi>
; DI void gemm8_tile(const bf16_t* __restrict__ Ab, int lda, const bf16_t* __restrict__ Bb, int ldb, int K, int brow, int bcol, const Epi epi,
;                    bool staged, bool has_next, const bf16_t* __restrict__ Abn, const bf16_t* __restrict__ Bbn) {
;     ...
;   for (int t = 0; t < nt; ++t) {
;     const int cur = t & 1;
;     const unsigned char* sa = smem + cur * G8_STAGE_B;
;     const unsigned char* sb = sa + G8_TILE_B;
; #pragma unroll
;     for (int ks = 0; ks < 2; ++ks) {
;       bf16x8 At[8], Bf[4];
;       Bf[0] = *(const bf16x8*)(sb + lds_byte2(wc * 64 + fr, ks * 32 + fq * 8));
;       At[0] = *(const bf16x8*)(sa + lds_byte2(wr * 128 + fr, ks * 32 + fq * 8));
; #pragma unroll
;       for (int n = 1; n < 4; ++n) Bf[n] = *(const bf16x8*)(sb + lds_byte2(wc * 64 + n * 16 + fr, ks * 32 + fq * 8));
; #pragma unroll
;       for (int m = 1; m < 8; ++m) At[m] = *(const bf16x8*)(sa + lds_byte2(wr * 128 + m * 16 + fr, ks * 32 + fq * 8));
;       {
;         __builtin_amdgcn_sched_barrier(0);
;         if (t + 1 < nt) { G8_STAGE_R(cur ^ 1, Ab + (t + 1) * 64, Bb + (t + 1) * 64, 2 * ks, 2 * ks + 2); }
;         else if (has_next) { G8_STAGE_R(0, Abn, Bbn, 2 * ks, 2 * ks + 2); }
;         __builtin_amdgcn_sched_barrier(0);
;       }
; #pragma unroll
;       for (int m = 0; m < 8; ++m)
; #pragma unroll
;         for (int n = 0; n < 4; ++n) acc[m][n] = MFMA16(At[m], Bf[n], acc[m][n]);
;       __builtin_amdgcn_sched_barrier(0);
;     }
;     asm volatile("s_waitcnt vmcnt(0)" ::: "memory");
;     __syncthreads();
;   }
.Lg80_462_last:
	v_mfma_f32_16x16x32_bf16 v[118:121], v[184:187], v[176:179], v[118:121]
	v_mfma_f32_16x16x32_bf16 v[114:117], v[184:187], v[180:183], v[114:117]
	v_mfma_f32_16x16x32_bf16 v[102:105], v[188:191], v[176:179], v[102:105]
	v_mfma_f32_16x16x32_bf16 v[98:101], v[188:191], v[180:183], v[98:101]
	v_mfma_f32_16x16x32_bf16 v[86:89], v[192:195], v[176:179], v[86:89]
	v_mfma_f32_16x16x32_bf16 v[82:85], v[192:195], v[180:183], v[82:85]
	v_mfma_f32_16x16x32_bf16 v[70:73], v[196:199], v[176:179], v[70:73]
	v_mfma_f32_16x16x32_bf16 v[66:69], v[196:199], v[180:183], v[66:69]
	v_mfma_f32_16x16x32_bf16 v[54:57], v[200:203], v[176:179], v[54:57]
	v_mfma_f32_16x16x32_bf16 v[50:53], v[200:203], v[180:183], v[50:53]
	v_mfma_f32_16x16x32_bf16 v[38:41], v[204:207], v[176:179], v[38:41]
	v_mfma_f32_16x16x32_bf16 v[34:37], v[204:207], v[180:183], v[34:37]
	v_mfma_f32_16x16x32_bf16 v[22:25], v[232:235], v[176:179], v[22:25]
	v_mfma_f32_16x16x32_bf16 v[18:21], v[232:235], v[180:183], v[18:21]
	v_mfma_f32_16x16x32_bf16 v[6:9], v[236:239], v[176:179], v[6:9]
	v_mfma_f32_16x16x32_bf16 v[2:5], v[236:239], v[180:183], v[2:5]
	s_add_i32 s0, 0, 0x18000
	v_add_u32_e32 v0, s0, v152
	v_add_u32_e32 v0, v0, v151
	v_add_u32_e32 v130, s30, v152
	v_add_u32_e32 v206, v130, v153
	ds_read_b128 v[130:133], v0
	ds_read_b128 v[134:137], v0 offset:2048
	ds_read_b128 v[138:141], v0 offset:4096
	ds_read_b128 v[142:145], v0 offset:6144
	v_add_u32_e32 v170, s30, v158
	v_add_u32_e32 v208, v170, v167
	v_add_u32_e32 v231, v170, v165
	v_add_u32_e32 v233, v170, v163
	v_add_u32_e32 v207, v170, v150
	ds_read_b128 v[150:153], v206
	ds_read_b128 v[158:161], v207
	v_add_u32_e32 v209, v170, v166
	ds_read_b128 v[166:169], v208
	ds_read_b128 v[174:177], v209
	v_add_u32_e32 v232, v170, v164
	ds_read_b128 v[182:185], v231
	ds_read_b128 v[190:193], v232
	v_add_u32_e32 v234, v170, v162
	ds_read_b128 v[198:201], v233
	ds_read_b128 v[202:205], v234
	v_cndmask_b32_e64 v162, 0, 1, s[54:55]
	v_cmp_ne_u32_e64 s[0:1], 1, v162
	s_andn2_b64 vcc, exec, s[54:55]
	s_cbranch_vccnz .LBB0_465
	v_readfirstlane_b32 s14, v157
	v_lshl_add_u64 v[162:163], s[10:11], 0, v[148:149]
	s_mov_b32 m0, s14
	v_readfirstlane_b32 s14, v156
	v_lshl_add_u64 v[148:149], s[38:39], 0, v[148:149]
	global_load_lds_dwordx4 v[162:163], off
	s_mov_b32 m0, s14
	v_readfirstlane_b32 s14, v155
	v_lshl_add_u64 v[164:165], s[10:11], 0, v[146:147]
	global_load_lds_dwordx4 v[148:149], off
	s_mov_b32 m0, s14
	v_readfirstlane_b32 s14, v154
	v_lshl_add_u64 v[146:147], s[38:39], 0, v[146:147]
	global_load_lds_dwordx4 v[164:165], off
	s_mov_b32 m0, s14
	s_nop 0
	global_load_lds_dwordx4 v[146:147], off

; #define MFMA16(a, b, c) __builtin_amdgcn_mfma_f32_16x16x32_bf16((a), (b), (c), 0, 0, 0)
; template <class Epi>
; DI void gemm8_tile(const bf16_t* __restrict__ Ab, int lda, const bf16_t* __restrict__ Bb, int ldb, int K, int brow, int bcol, const Epi epi,
;                    bool staged, bool has_next, const bf16_t* __restrict__ Abn, const bf16_t* __restrict__ Bbn) {
;     ...
;   for (int t = 0; t < nt; ++t) {
;     const int cur = t & 1;
;     const unsigned char* sa = smem + cur * G8_STAGE_B;
;     const unsigned char* sb = sa + G8_TILE_B;
; #pragma unroll
;     for (int ks = 0; ks < 2; ++ks) {
;       bf16x8 At[8], Bf[4];
;       Bf[0] = *(const bf16x8*)(sb + lds_byte2(wc * 64 + fr, ks * 32 + fq * 8));
;       At[0] = *(const bf16x8*)(sa + lds_byte2(wr * 128 + fr, ks * 32 + fq * 8));
; #pragma unroll
;       for (int n = 1; n < 4; ++n) Bf[n] = *(const bf16x8*)(sb + lds_byte2(wc * 64 + n * 16 + fr, ks * 32 + fq * 8));
; #pragma unroll
;       for (int m = 1; m < 8; ++m) At[m] = *(const bf16x8*)(sa + lds_byte2(wr * 128 + m * 16 + fr, ks * 32 + fq * 8));
;       {
;         __builtin_amdgcn_sched_barrier(0);
;         if (t + 1 < nt) { G8_STAGE_R(cur ^ 1, Ab + (t + 1) * 64, Bb + (t + 1) * 64, 2 * ks, 2 * ks + 2); }
;         else if (has_next) { G8_STAGE_R(0, Abn, Bbn, 2 * ks, 2 * ks + 2); }
;         __builtin_amdgcn_sched_barrier(0);
;       }
; #pragma unroll
;       for (int m = 0; m < 8; ++m)
; #pragma unroll
;         for (int n = 0; n < 4; ++n) acc[m][n] = MFMA16(At[m], Bf[n], acc[m][n]);
;       __builtin_amdgcn_sched_barrier(0);
;     }
;     asm volatile("s_waitcnt vmcnt(0)" ::: "memory");
;     __syncthreads();
;   }
.Lg80_483_last:
	v_mfma_f32_16x16x32_bf16 v[118:121], v[174:177], v[166:169], v[118:121]
	v_mfma_f32_16x16x32_bf16 v[114:117], v[174:177], v[170:173], v[114:117]
	v_mfma_f32_16x16x32_bf16 v[102:105], v[186:189], v[166:169], v[102:105]
	v_mfma_f32_16x16x32_bf16 v[98:101], v[186:189], v[170:173], v[98:101]
	v_mfma_f32_16x16x32_bf16 v[86:89], v[190:193], v[166:169], v[86:89]
	v_mfma_f32_16x16x32_bf16 v[82:85], v[190:193], v[170:173], v[82:85]
	v_mfma_f32_16x16x32_bf16 v[70:73], v[212:215], v[166:169], v[70:73]
	v_mfma_f32_16x16x32_bf16 v[66:69], v[212:215], v[170:173], v[66:69]
	v_mfma_f32_16x16x32_bf16 v[54:57], v[222:225], v[166:169], v[54:57]
	v_mfma_f32_16x16x32_bf16 v[50:53], v[222:225], v[170:173], v[50:53]
	v_mfma_f32_16x16x32_bf16 v[38:41], v[226:229], v[166:169], v[38:41]
	v_mfma_f32_16x16x32_bf16 v[34:37], v[226:229], v[170:173], v[34:37]
	v_mfma_f32_16x16x32_bf16 v[22:25], v[230:233], v[166:169], v[22:25]
	v_mfma_f32_16x16x32_bf16 v[18:21], v[230:233], v[170:173], v[18:21]
	v_mfma_f32_16x16x32_bf16 v[6:9], v[234:237], v[166:169], v[6:9]
	v_mfma_f32_16x16x32_bf16 v[2:5], v[234:237], v[170:173], v[2:5]
	s_add_i32 s0, 0, 0x18000
	v_add_u32_e32 v0, s0, v155
	v_add_u32_e32 v0, v0, v153
	v_add_u32_e32 v130, s30, v155
	v_add_u32_e32 v190, v130, v156
	ds_read_b128 v[130:133], v0
	ds_read_b128 v[134:137], v0 offset:2048
	ds_read_b128 v[138:141], v0 offset:4096
	ds_read_b128 v[142:145], v0 offset:6144
	v_add_u32_e32 v154, s30, v154
	v_add_u32_e32 v192, v154, v152
	v_add_u32_e32 v207, v154, v149
	v_add_u32_e32 v209, v154, v147
	v_add_u32_e32 v191, v154, v150
	ds_read_b128 v[174:177], v190
	ds_read_b128 v[166:169], v191
	v_add_u32_e32 v193, v154, v151
	ds_read_b128 v[170:173], v192
	ds_read_b128 v[158:161], v193
	v_add_u32_e32 v208, v154, v148
	ds_read_b128 v[162:165], v207
	ds_read_b128 v[150:153], v208
	v_add_u32_e32 v212, v154, v146
	ds_read_b128 v[154:157], v209
	ds_read_b128 v[146:149], v212
	v_cndmask_b32_e64 v186, 0, 1, s[14:15]
	v_cmp_ne_u32_e64 s[0:1], 1, v186
	s_andn2_b64 vcc, exec, s[14:15]
	s_cbranch_vccnz .LBB0_486
	v_readfirstlane_b32 s14, v185
	v_lshl_add_u64 v[188:189], s[10:11], 0, v[178:179]
	v_lshl_add_u64 v[178:179], s[8:9], 0, v[178:179]
	s_mov_b32 m0, s14
	v_readfirstlane_b32 s14, v184
	global_load_lds_dwordx4 v[178:179], off
	s_mov_b32 m0, s14
	v_readfirstlane_b32 s14, v183
	v_lshl_add_u64 v[186:187], s[10:11], 0, v[180:181]
	v_lshl_add_u64 v[180:181], s[8:9], 0, v[180:181]
	global_load_lds_dwordx4 v[188:189], off
	s_mov_b32 m0, s14
	v_readfirstlane_b32 s14, v182
	global_load_lds_dwordx4 v[180:181], off
	s_mov_b32 m0, s14
	s_nop 0
	global_load_lds_dwordx4 v[186:187], off

; #define MFMA16(a, b, c) __builtin_amdgcn_mfma_f32_16x16x32_bf16((a), (b), (c), 0, 0, 0)
; template <class Epi>
; DI void gemm8_tile(const bf16_t* __restrict__ Ab, int lda, const bf16_t* __restrict__ Bb, int ldb, int K, int brow, int bcol, const Epi epi,
;                    bool staged, bool has_next, const bf16_t* __restrict__ Abn, const bf16_t* __restrict__ Bbn) {
;     ...
;   for (int t = 0; t < nt; ++t) {
;     const int cur = t & 1;
;     const unsigned char* sa = smem + cur * G8_STAGE_B;
;     const unsigned char* sb = sa + G8_TILE_B;
; #pragma unroll
;     for (int ks = 0; ks < 2; ++ks) {
;       bf16x8 At[8], Bf[4];
;       Bf[0] = *(const bf16x8*)(sb + lds_byte2(wc * 64 + fr, ks * 32 + fq * 8));
;       At[0] = *(const bf16x8*)(sa + lds_byte2(wr * 128 + fr, ks * 32 + fq * 8));
; #pragma unroll
;       for (int n = 1; n < 4; ++n) Bf[n] = *(const bf16x8*)(sb + lds_byte2(wc * 64 + n * 16 + fr, ks * 32 + fq * 8));
; #pragma unroll
;       for (int m = 1; m < 8; ++m) At[m] = *(const bf16x8*)(sa + lds_byte2(wr * 128 + m * 16 + fr, ks * 32 + fq * 8));
;       {
;         __builtin_amdgcn_sched_barrier(0);
;         if (t + 1 < nt) { G8_STAGE_R(cur ^ 1, Ab + (t + 1) * 64, Bb + (t + 1) * 64, 2 * ks, 2 * ks + 2); }
;         else if (has_next) { G8_STAGE_R(0, Abn, Bbn, 2 * ks, 2 * ks + 2); }
;         __builtin_amdgcn_sched_barrier(0);
;       }
; #pragma unroll
;       for (int m = 0; m < 8; ++m)
; #pragma unroll
;         for (int n = 0; n < 4; ++n) acc[m][n] = MFMA16(At[m], Bf[n], acc[m][n]);
;       __builtin_amdgcn_sched_barrier(0);
;     }
;     asm volatile("s_waitcnt vmcnt(0)" ::: "memory");
;     __syncthreads();
;   }
.Lg80_650_last:
	v_mfma_f32_16x16x32_bf16 v[118:121], v[174:177], v[166:169], v[118:121]
	v_mfma_f32_16x16x32_bf16 v[114:117], v[174:177], v[170:173], v[114:117]
	v_mfma_f32_16x16x32_bf16 v[102:105], v[186:189], v[166:169], v[102:105]
	v_mfma_f32_16x16x32_bf16 v[98:101], v[186:189], v[170:173], v[98:101]
	v_mfma_f32_16x16x32_bf16 v[86:89], v[202:205], v[166:169], v[86:89]
	v_mfma_f32_16x16x32_bf16 v[82:85], v[202:205], v[170:173], v[82:85]
	v_mfma_f32_16x16x32_bf16 v[70:73], v[206:209], v[166:169], v[70:73]
	v_mfma_f32_16x16x32_bf16 v[66:69], v[206:209], v[170:173], v[66:69]
	v_mfma_f32_16x16x32_bf16 v[54:57], v[212:215], v[166:169], v[54:57]
	v_mfma_f32_16x16x32_bf16 v[50:53], v[212:215], v[170:173], v[50:53]
	v_mfma_f32_16x16x32_bf16 v[38:41], v[222:225], v[166:169], v[38:41]
	v_mfma_f32_16x16x32_bf16 v[34:37], v[222:225], v[170:173], v[34:37]
	v_mfma_f32_16x16x32_bf16 v[22:25], v[226:229], v[166:169], v[22:25]
	v_mfma_f32_16x16x32_bf16 v[18:21], v[226:229], v[170:173], v[18:21]
	v_mfma_f32_16x16x32_bf16 v[6:9], v[230:233], v[166:169], v[6:9]
	v_mfma_f32_16x16x32_bf16 v[2:5], v[230:233], v[170:173], v[2:5]
	s_add_i32 s0, 0, 0x18000
	v_add_u32_e32 v0, s0, v155
	v_add_u32_e32 v0, v0, v153
	v_add_u32_e32 v130, s30, v155
	v_add_u32_e32 v186, v130, v156
	ds_read_b128 v[130:133], v0
	ds_read_b128 v[134:137], v0 offset:2048
	ds_read_b128 v[138:141], v0 offset:4096
	ds_read_b128 v[142:145], v0 offset:6144
	v_add_u32_e32 v154, s30, v154
	v_add_u32_e32 v203, v154, v152
	v_add_u32_e32 v205, v154, v149
	v_add_u32_e32 v207, v154, v147
	v_add_u32_e32 v202, v154, v150
	ds_read_b128 v[174:177], v186
	ds_read_b128 v[166:169], v202
	v_add_u32_e32 v204, v154, v151
	ds_read_b128 v[170:173], v203
	ds_read_b128 v[158:161], v204
	v_add_u32_e32 v206, v154, v148
	ds_read_b128 v[162:165], v205
	ds_read_b128 v[150:153], v206
	v_add_u32_e32 v208, v154, v146
	ds_read_b128 v[154:157], v207
	ds_read_b128 v[146:149], v208
	v_cndmask_b32_e64 v187, 0, 1, s[12:13]
	v_cmp_ne_u32_e64 s[0:1], 1, v187
	s_andn2_b64 vcc, exec, s[12:13]
	s_cbranch_vccnz .LBB0_653
	v_readfirstlane_b32 s12, v185
	v_lshl_add_u64 v[188:189], s[8:9], 0, v[180:181]
	s_mov_b32 m0, s12
	v_readfirstlane_b32 s12, v184
	v_lshl_add_u64 v[180:181], s[10:11], 0, v[180:181]
	global_load_lds_dwordx4 v[188:189], off
	s_mov_b32 m0, s12
	v_readfirstlane_b32 s12, v183
	v_lshl_add_u64 v[212:213], s[8:9], 0, v[178:179]
	global_load_lds_dwordx4 v[180:181], off
	s_mov_b32 m0, s12
	v_readfirstlane_b32 s12, v182
	v_lshl_add_u64 v[178:179], s[10:11], 0, v[178:179]
	global_load_lds_dwordx4 v[212:213], off
	s_mov_b32 m0, s12
	s_nop 0
	global_load_lds_dwordx4 v[178:179], off

; #define MFMA16(a, b, c) __builtin_amdgcn_mfma_f32_16x16x32_bf16((a), (b), (c), 0, 0, 0)
; template <class Epi>
; DI void gemm8_tile(const bf16_t* __restrict__ Ab, int lda, const bf16_t* __restrict__ Bb, int ldb, int K, int brow, int bcol, const Epi epi,
;                    bool staged, bool has_next, const bf16_t* __restrict__ Abn, const bf16_t* __restrict__ Bbn) {
;     ...
;   for (int t = 0; t < nt; ++t) {
;     const int cur = t & 1;
;     const unsigned char* sa = smem + cur * G8_STAGE_B;
;     const unsigned char* sb = sa + G8_TILE_B;
; #pragma unroll
;     for (int ks = 0; ks < 2; ++ks) {
;       bf16x8 At[8], Bf[4];
;       Bf[0] = *(const bf16x8*)(sb + lds_byte2(wc * 64 + fr, ks * 32 + fq * 8));
;       At[0] = *(const bf16x8*)(sa + lds_byte2(wr * 128 + fr, ks * 32 + fq * 8));
; #pragma unroll
;       for (int n = 1; n < 4; ++n) Bf[n] = *(const bf16x8*)(sb + lds_byte2(wc * 64 + n * 16 + fr, ks * 32 + fq * 8));
; #pragma unroll
;       for (int m = 1; m < 8; ++m) At[m] = *(const bf16x8*)(sa + lds_byte2(wr * 128 + m * 16 + fr, ks * 32 + fq * 8));
;       {
;         __builtin_amdgcn_sched_barrier(0);
;         if (t + 1 < nt) { G8_STAGE_R(cur ^ 1, Ab + (t + 1) * 64, Bb + (t + 1) * 64, 2 * ks, 2 * ks + 2); }
;         else if (has_next) { G8_STAGE_R(0, Abn, Bbn, 2 * ks, 2 * ks + 2); }
;         __builtin_amdgcn_sched_barrier(0);
;       }
; #pragma unroll
;       for (int m = 0; m < 8; ++m)
; #pragma unroll
;         for (int n = 0; n < 4; ++n) acc[m][n] = MFMA16(At[m], Bf[n], acc[m][n]);
;       __builtin_amdgcn_sched_barrier(0);
;     }
;     asm volatile("s_waitcnt vmcnt(0)" ::: "memory");
;     __syncthreads();
;   }
.Lg80_1254_last:
	v_mfma_f32_16x16x32_bf16 v[118:121], v[174:177], v[166:169], v[118:121]
	v_mfma_f32_16x16x32_bf16 v[114:117], v[174:177], v[170:173], v[114:117]
	v_mfma_f32_16x16x32_bf16 v[102:105], v[204:207], v[166:169], v[102:105]
	v_mfma_f32_16x16x32_bf16 v[98:101], v[204:207], v[170:173], v[98:101]
	v_mfma_f32_16x16x32_bf16 v[86:89], v[212:215], v[166:169], v[86:89]
	v_mfma_f32_16x16x32_bf16 v[82:85], v[212:215], v[170:173], v[82:85]
	v_mfma_f32_16x16x32_bf16 v[70:73], v[222:225], v[166:169], v[70:73]
	v_mfma_f32_16x16x32_bf16 v[66:69], v[222:225], v[170:173], v[66:69]
	v_mfma_f32_16x16x32_bf16 v[54:57], v[226:229], v[166:169], v[54:57]
	v_mfma_f32_16x16x32_bf16 v[50:53], v[226:229], v[170:173], v[50:53]
	v_mfma_f32_16x16x32_bf16 v[38:41], v[230:233], v[166:169], v[38:41]
	v_mfma_f32_16x16x32_bf16 v[34:37], v[230:233], v[170:173], v[34:37]
	v_mfma_f32_16x16x32_bf16 v[22:25], v[234:237], v[166:169], v[22:25]
	v_mfma_f32_16x16x32_bf16 v[18:21], v[234:237], v[170:173], v[18:21]
	v_mfma_f32_16x16x32_bf16 v[6:9], v[238:241], v[166:169], v[6:9]
	v_mfma_f32_16x16x32_bf16 v[2:5], v[238:241], v[170:173], v[2:5]
	s_add_i32 s0, 0, 0x18000
	v_add_u32_e32 v130, s0, v155
	v_add_u32_e32 v204, v130, v153
	v_add_u32_e32 v130, s30, v155
	v_add_u32_e32 v205, v130, v156
	ds_read_b128 v[130:133], v204
	ds_read_b128 v[134:137], v204 offset:2048
	ds_read_b128 v[138:141], v204 offset:4096
	ds_read_b128 v[142:145], v204 offset:6144
	v_add_u32_e32 v154, s30, v154
	v_add_u32_e32 v207, v154, v152
	v_add_u32_e32 v209, v154, v149
	v_add_u32_e32 v213, v154, v147
	v_add_u32_e32 v206, v154, v150
	ds_read_b128 v[174:177], v205
	ds_read_b128 v[166:169], v206
	v_add_u32_e32 v208, v154, v151
	ds_read_b128 v[170:173], v207
	ds_read_b128 v[158:161], v208
	v_add_u32_e32 v212, v154, v148
	ds_read_b128 v[162:165], v209
	ds_read_b128 v[150:153], v212
	v_add_u32_e32 v214, v154, v146
	ds_read_b128 v[154:157], v213
	ds_read_b128 v[146:149], v214
	v_cndmask_b32_e64 v215, 0, 1, s[14:15]
	v_cmp_ne_u32_e64 s[0:1], 1, v215
	s_andn2_b64 vcc, exec, s[14:15]
	s_cbranch_vccnz .LBB0_1257
	v_readfirstlane_b32 s14, v203
	v_lshl_add_u64 v[184:185], v[184:185], 1, s[10:11]
	s_mov_b32 m0, s14
	v_readfirstlane_b32 s14, v202
	v_lshl_add_u64 v[186:187], v[186:187], 1, s[12:13]
	global_load_lds_dwordx4 v[184:185], off
	s_mov_b32 m0, s14
	v_readfirstlane_b32 s14, v201
	v_lshl_add_u64 v[188:189], v[188:189], 1, s[10:11]
	global_load_lds_dwordx4 v[186:187], off
	s_mov_b32 m0, s14
	v_readfirstlane_b32 s14, v200
	v_lshl_add_u64 v[190:191], v[190:191], 1, s[12:13]
	global_load_lds_dwordx4 v[188:189], off
	s_mov_b32 m0, s14
	s_nop 0
	global_load_lds_dwordx4 v[190:191], off

; #define MFMA16(a, b, c) __builtin_amdgcn_mfma_f32_16x16x32_bf16((a), (b), (c), 0, 0, 0)
; template <class Epi>
; DI void gemm8_tile(const bf16_t* __restrict__ Ab, int lda, const bf16_t* __restrict__ Bb, int ldb, int K, int brow, int bcol, const Epi epi,
;                    bool staged, bool has_next, const bf16_t* __restrict__ Abn, const bf16_t* __restrict__ Bbn) {
;     ...
;   for (int t = 0; t < nt; ++t) {
;     const int cur = t & 1;
;     const unsigned char* sa = smem + cur * G8_STAGE_B;
;     const unsigned char* sb = sa + G8_TILE_B;
; #pragma unroll
;     for (int ks = 0; ks < 2; ++ks) {
;       bf16x8 At[8], Bf[4];
;       Bf[0] = *(const bf16x8*)(sb + lds_byte2(wc * 64 + fr, ks * 32 + fq * 8));
;       At[0] = *(const bf16x8*)(sa + lds_byte2(wr * 128 + fr, ks * 32 + fq * 8));
; #pragma unroll
;       for (int n = 1; n < 4; ++n) Bf[n] = *(const bf16x8*)(sb + lds_byte2(wc * 64 + n * 16 + fr, ks * 32 + fq * 8));
; #pragma unroll
;       for (int m = 1; m < 8; ++m) At[m] = *(const bf16x8*)(sa + lds_byte2(wr * 128 + m * 16 + fr, ks * 32 + fq * 8));
;       {
;         __builtin_amdgcn_sched_barrier(0);
;         if (t + 1 < nt) { G8_STAGE_R(cur ^ 1, Ab + (t + 1) * 64, Bb + (t + 1) * 64, 2 * ks, 2 * ks + 2); }
;         else if (has_next) { G8_STAGE_R(0, Abn, Bbn, 2 * ks, 2 * ks + 2); }
;         __builtin_amdgcn_sched_barrier(0);
;       }
; #pragma unroll
;       for (int m = 0; m < 8; ++m)
; #pragma unroll
;         for (int n = 0; n < 4; ++n) acc[m][n] = MFMA16(At[m], Bf[n], acc[m][n]);
;       __builtin_amdgcn_sched_barrier(0);
;     }
;     asm volatile("s_waitcnt vmcnt(0)" ::: "memory");
;     __syncthreads();
;   }
.Lg80_1510_last:
	v_mfma_f32_16x16x32_bf16 v[118:121], v[174:177], v[166:169], v[118:121]
	v_mfma_f32_16x16x32_bf16 v[114:117], v[174:177], v[170:173], v[114:117]
	v_mfma_f32_16x16x32_bf16 v[102:105], v[190:193], v[166:169], v[102:105]
	v_mfma_f32_16x16x32_bf16 v[98:101], v[190:193], v[170:173], v[98:101]
	v_mfma_f32_16x16x32_bf16 v[86:89], v[212:215], v[166:169], v[86:89]
	v_mfma_f32_16x16x32_bf16 v[82:85], v[212:215], v[170:173], v[82:85]
	v_mfma_f32_16x16x32_bf16 v[70:73], v[222:225], v[166:169], v[70:73]
	v_mfma_f32_16x16x32_bf16 v[66:69], v[222:225], v[170:173], v[66:69]
	v_mfma_f32_16x16x32_bf16 v[54:57], v[226:229], v[166:169], v[54:57]
	v_mfma_f32_16x16x32_bf16 v[50:53], v[226:229], v[170:173], v[50:53]
	v_mfma_f32_16x16x32_bf16 v[38:41], v[230:233], v[166:169], v[38:41]
	v_mfma_f32_16x16x32_bf16 v[34:37], v[230:233], v[170:173], v[34:37]
	v_mfma_f32_16x16x32_bf16 v[22:25], v[234:237], v[166:169], v[22:25]
	v_mfma_f32_16x16x32_bf16 v[18:21], v[234:237], v[170:173], v[18:21]
	v_mfma_f32_16x16x32_bf16 v[6:9], v[238:241], v[166:169], v[6:9]
	v_mfma_f32_16x16x32_bf16 v[2:5], v[238:241], v[170:173], v[2:5]
	s_add_i32 s0, 0, 0x18000
	v_add_u32_e32 v130, s0, v155
	v_add_u32_e32 v190, v130, v153
	v_add_u32_e32 v130, s30, v155
	v_add_u32_e32 v191, v130, v156
	ds_read_b128 v[130:133], v190
	ds_read_b128 v[134:137], v190 offset:2048
	ds_read_b128 v[138:141], v190 offset:4096
	ds_read_b128 v[142:145], v190 offset:6144
	v_add_u32_e32 v154, s30, v154
	v_add_u32_e32 v193, v154, v152
	v_add_u32_e32 v212, v154, v149
	v_add_u32_e32 v214, v154, v147
	v_add_u32_e32 v192, v154, v150
	ds_read_b128 v[174:177], v191
	ds_read_b128 v[166:169], v192
	v_add_u32_e32 v209, v154, v151
	ds_read_b128 v[170:173], v193
	ds_read_b128 v[158:161], v209
	v_add_u32_e32 v213, v154, v148
	ds_read_b128 v[162:165], v212
	ds_read_b128 v[150:153], v213
	v_add_u32_e32 v215, v154, v146
	ds_read_b128 v[154:157], v214
	ds_read_b128 v[146:149], v215
	v_cndmask_b32_e64 v222, 0, 1, s[38:39]
	v_cmp_ne_u32_e64 s[0:1], 1, v222
	s_andn2_b64 vcc, exec, s[38:39]
	s_movk_i32 s79, 0xffe0
	s_cbranch_vccnz .LBB0_1513
	v_readfirstlane_b32 s9, v189
	v_lshl_add_u64 v[178:179], v[178:179], 1, s[10:11]
	s_mov_b32 m0, s9
	v_readfirstlane_b32 s9, v188
	v_lshl_add_u64 v[180:181], v[180:181], 1, s[12:13]
	global_load_lds_dwordx4 v[178:179], off
	s_mov_b32 m0, s9
	v_readfirstlane_b32 s9, v187
	v_lshl_add_u64 v[182:183], v[182:183], 1, s[10:11]
	global_load_lds_dwordx4 v[180:181], off
	s_mov_b32 m0, s9
	v_readfirstlane_b32 s9, v186
	v_lshl_add_u64 v[184:185], v[184:185], 1, s[12:13]
	global_load_lds_dwordx4 v[182:183], off
	s_mov_b32 m0, s9
	s_nop 0
	global_load_lds_dwordx4 v[184:185], off

; #define MFMA16(a, b, c) __builtin_amdgcn_mfma_f32_16x16x32_bf16((a), (b), (c), 0, 0, 0)
; template <class Epi>
; DI void gemm8_tile(const bf16_t* __restrict__ Ab, int lda, const bf16_t* __restrict__ Bb, int ldb, int K, int brow, int bcol, const Epi epi,
;                    bool staged, bool has_next, const bf16_t* __restrict__ Abn, const bf16_t* __restrict__ Bbn) {
;     ...
;   for (int t = 0; t < nt; ++t) {
;     const int cur = t & 1;
;     const unsigned char* sa = smem + cur * G8_STAGE_B;
;     const unsigned char* sb = sa + G8_TILE_B;
; #pragma unroll
;     for (int ks = 0; ks < 2; ++ks) {
;       bf16x8 At[8], Bf[4];
;       Bf[0] = *(const bf16x8*)(sb + lds_byte2(wc * 64 + fr, ks * 32 + fq * 8));
;       At[0] = *(const bf16x8*)(sa + lds_byte2(wr * 128 + fr, ks * 32 + fq * 8));
; #pragma unroll
;       for (int n = 1; n < 4; ++n) Bf[n] = *(const bf16x8*)(sb + lds_byte2(wc * 64 + n * 16 + fr, ks * 32 + fq * 8));
; #pragma unroll
;       for (int m = 1; m < 8; ++m) At[m] = *(const bf16x8*)(sa + lds_byte2(wr * 128 + m * 16 + fr, ks * 32 + fq * 8));
;       {
;         __builtin_amdgcn_sched_barrier(0);
;         if (t + 1 < nt) { G8_STAGE_R(cur ^ 1, Ab + (t + 1) * 64, Bb + (t + 1) * 64, 2 * ks, 2 * ks + 2); }
;         else if (has_next) { G8_STAGE_R(0, Abn, Bbn, 2 * ks, 2 * ks + 2); }
;         __builtin_amdgcn_sched_barrier(0);
;       }
; #pragma unroll
;       for (int m = 0; m < 8; ++m)
; #pragma unroll
;         for (int n = 0; n < 4; ++n) acc[m][n] = MFMA16(At[m], Bf[n], acc[m][n]);
;       __builtin_amdgcn_sched_barrier(0);
;     }
;     asm volatile("s_waitcnt vmcnt(0)" ::: "memory");
;     __syncthreads();
;   }
.Lg80_1673_last:
	v_mfma_f32_16x16x32_bf16 v[118:121], v[184:187], v[176:179], v[118:121]
	v_mfma_f32_16x16x32_bf16 v[114:117], v[184:187], v[180:183], v[114:117]
	v_mfma_f32_16x16x32_bf16 v[102:105], v[188:191], v[176:179], v[102:105]
	v_mfma_f32_16x16x32_bf16 v[98:101], v[188:191], v[180:183], v[98:101]
	v_mfma_f32_16x16x32_bf16 v[86:89], v[192:195], v[176:179], v[86:89]
	v_mfma_f32_16x16x32_bf16 v[82:85], v[192:195], v[180:183], v[82:85]
	v_mfma_f32_16x16x32_bf16 v[70:73], v[196:199], v[176:179], v[70:73]
	v_mfma_f32_16x16x32_bf16 v[66:69], v[196:199], v[180:183], v[66:69]
	v_mfma_f32_16x16x32_bf16 v[54:57], v[200:203], v[176:179], v[54:57]
	v_mfma_f32_16x16x32_bf16 v[50:53], v[200:203], v[180:183], v[50:53]
	v_mfma_f32_16x16x32_bf16 v[38:41], v[204:207], v[176:179], v[38:41]
	v_mfma_f32_16x16x32_bf16 v[34:37], v[204:207], v[180:183], v[34:37]
	v_mfma_f32_16x16x32_bf16 v[22:25], v[232:235], v[176:179], v[22:25]
	v_mfma_f32_16x16x32_bf16 v[18:21], v[232:235], v[180:183], v[18:21]
	v_mfma_f32_16x16x32_bf16 v[6:9], v[236:239], v[176:179], v[6:9]
	v_mfma_f32_16x16x32_bf16 v[2:5], v[236:239], v[180:183], v[2:5]
	s_add_i32 s0, 0, 0x18000
	v_add_u32_e32 v0, s0, v153
	v_add_u32_e32 v0, v0, v151
	v_add_u32_e32 v130, s30, v153
	v_add_u32_e32 v206, v130, v158
	ds_read_b128 v[130:133], v0
	ds_read_b128 v[134:137], v0 offset:2048
	ds_read_b128 v[138:141], v0 offset:4096
	ds_read_b128 v[142:145], v0 offset:6144
	v_add_u32_e32 v170, s30, v152
	v_add_u32_e32 v208, v170, v167
	v_add_u32_e32 v231, v170, v165
	v_add_u32_e32 v233, v170, v163
	v_add_u32_e32 v207, v170, v150
	ds_read_b128 v[150:153], v206
	ds_read_b128 v[158:161], v207
	v_add_u32_e32 v209, v170, v166
	ds_read_b128 v[166:169], v208
	ds_read_b128 v[174:177], v209
	v_add_u32_e32 v232, v170, v164
	ds_read_b128 v[182:185], v231
	ds_read_b128 v[190:193], v232
	v_add_u32_e32 v234, v170, v162
	ds_read_b128 v[198:201], v233
	ds_read_b128 v[202:205], v234
	v_cndmask_b32_e64 v162, 0, 1, s[12:13]
	v_cmp_ne_u32_e64 s[0:1], 1, v162
	s_andn2_b64 vcc, exec, s[12:13]
	s_cbranch_vccnz .LBB0_1676
	v_readfirstlane_b32 s12, v157
	v_lshl_add_u64 v[162:163], s[8:9], 0, v[148:149]
	s_mov_b32 m0, s12
	v_readfirstlane_b32 s12, v156
	v_lshl_add_u64 v[148:149], s[10:11], 0, v[148:149]
	global_load_lds_dwordx4 v[162:163], off
	s_mov_b32 m0, s12
	v_readfirstlane_b32 s12, v155
	v_lshl_add_u64 v[164:165], s[8:9], 0, v[146:147]
	global_load_lds_dwordx4 v[148:149], off
	s_mov_b32 m0, s12
	v_readfirstlane_b32 s12, v154
	v_lshl_add_u64 v[146:147], s[10:11], 0, v[146:147]
	global_load_lds_dwordx4 v[164:165], off
	s_mov_b32 m0, s12
	s_nop 0
	global_load_lds_dwordx4 v[146:147], off

; #define MFMA16(a, b, c) __builtin_amdgcn_mfma_f32_16x16x32_bf16((a), (b), (c), 0, 0, 0)
; template <class Epi>
; DI void gemm8_tile(const bf16_t* __restrict__ Ab, int lda, const bf16_t* __restrict__ Bb, int ldb, int K, int brow, int bcol, const Epi epi,
;                    bool staged, bool has_next, const bf16_t* __restrict__ Abn, const bf16_t* __restrict__ Bbn) {
;     ...
;   for (int t = 0; t < nt; ++t) {
;     const int cur = t & 1;
;     const unsigned char* sa = smem + cur * G8_STAGE_B;
;     const unsigned char* sb = sa + G8_TILE_B;
; #pragma unroll
;     for (int ks = 0; ks < 2; ++ks) {
;       bf16x8 At[8], Bf[4];
;       Bf[0] = *(const bf16x8*)(sb + lds_byte2(wc * 64 + fr, ks * 32 + fq * 8));
;       At[0] = *(const bf16x8*)(sa + lds_byte2(wr * 128 + fr, ks * 32 + fq * 8));
; #pragma unroll
;       for (int n = 1; n < 4; ++n) Bf[n] = *(const bf16x8*)(sb + lds_byte2(wc * 64 + n * 16 + fr, ks * 32 + fq * 8));
; #pragma unroll
;       for (int m = 1; m < 8; ++m) At[m] = *(const bf16x8*)(sa + lds_byte2(wr * 128 + m * 16 + fr, ks * 32 + fq * 8));
;       {
;         __builtin_amdgcn_sched_barrier(0);
;         if (t + 1 < nt) { G8_STAGE_R(cur ^ 1, Ab + (t + 1) * 64, Bb + (t + 1) * 64, 2 * ks, 2 * ks + 2); }
;         else if (has_next) { G8_STAGE_R(0, Abn, Bbn, 2 * ks, 2 * ks + 2); }
;         __builtin_amdgcn_sched_barrier(0);
;       }
; #pragma unroll
;       for (int m = 0; m < 8; ++m)
; #pragma unroll
;         for (int n = 0; n < 4; ++n) acc[m][n] = MFMA16(At[m], Bf[n], acc[m][n]);
;       __builtin_amdgcn_sched_barrier(0);
;     }
;     asm volatile("s_waitcnt vmcnt(0)" ::: "memory");
;     __syncthreads();
;   }
.Lg80_1695_last:
	v_mfma_f32_16x16x32_bf16 v[118:121], v[174:177], v[166:169], v[118:121]
	v_mfma_f32_16x16x32_bf16 v[114:117], v[174:177], v[170:173], v[114:117]
	v_mfma_f32_16x16x32_bf16 v[102:105], v[186:189], v[166:169], v[102:105]
	v_mfma_f32_16x16x32_bf16 v[98:101], v[186:189], v[170:173], v[98:101]
	v_mfma_f32_16x16x32_bf16 v[86:89], v[190:193], v[166:169], v[86:89]
	v_mfma_f32_16x16x32_bf16 v[82:85], v[190:193], v[170:173], v[82:85]
	v_mfma_f32_16x16x32_bf16 v[70:73], v[212:215], v[166:169], v[70:73]
	v_mfma_f32_16x16x32_bf16 v[66:69], v[212:215], v[170:173], v[66:69]
	v_mfma_f32_16x16x32_bf16 v[54:57], v[222:225], v[166:169], v[54:57]
	v_mfma_f32_16x16x32_bf16 v[50:53], v[222:225], v[170:173], v[50:53]
	v_mfma_f32_16x16x32_bf16 v[38:41], v[226:229], v[166:169], v[38:41]
	v_mfma_f32_16x16x32_bf16 v[34:37], v[226:229], v[170:173], v[34:37]
	v_mfma_f32_16x16x32_bf16 v[22:25], v[230:233], v[166:169], v[22:25]
	v_mfma_f32_16x16x32_bf16 v[18:21], v[230:233], v[170:173], v[18:21]
	v_mfma_f32_16x16x32_bf16 v[6:9], v[234:237], v[166:169], v[6:9]
	v_mfma_f32_16x16x32_bf16 v[2:5], v[234:237], v[170:173], v[2:5]
	s_add_i32 s0, 0, 0x18000
	v_add_u32_e32 v0, s0, v155
	v_add_u32_e32 v0, v0, v153
	v_add_u32_e32 v130, s30, v155
	v_add_u32_e32 v190, v130, v156
	ds_read_b128 v[130:133], v0
	ds_read_b128 v[134:137], v0 offset:2048
	ds_read_b128 v[138:141], v0 offset:4096
	ds_read_b128 v[142:145], v0 offset:6144
	v_add_u32_e32 v174, s30, v154
	v_add_u32_e32 v192, v174, v152
	v_add_u32_e32 v207, v174, v149
	v_add_u32_e32 v209, v174, v147
	v_add_u32_e32 v191, v174, v150
	ds_read_b128 v[170:173], v190
	ds_read_b128 v[162:165], v191
	v_add_u32_e32 v193, v174, v151
	ds_read_b128 v[166:169], v192
	ds_read_b128 v[154:157], v193
	v_add_u32_e32 v208, v174, v148
	ds_read_b128 v[158:161], v207
	ds_read_b128 v[150:153], v208
	v_add_u32_e32 v212, v174, v146
	ds_read_b128 v[174:177], v209
	ds_read_b128 v[146:149], v212
	v_cndmask_b32_e64 v186, 0, 1, s[14:15]
	v_cmp_ne_u32_e64 s[0:1], 1, v186
	s_andn2_b64 vcc, exec, s[14:15]
	s_cbranch_vccnz .LBB0_1698
	v_readfirstlane_b32 s14, v185
	v_lshl_add_u64 v[188:189], s[6:7], 0, v[178:179]
	v_lshl_add_u64 v[178:179], s[4:5], 0, v[178:179]
	s_mov_b32 m0, s14
	v_readfirstlane_b32 s14, v184
	global_load_lds_dwordx4 v[178:179], off
	s_mov_b32 m0, s14
	v_readfirstlane_b32 s14, v183
	v_lshl_add_u64 v[186:187], s[6:7], 0, v[180:181]
	v_lshl_add_u64 v[180:181], s[4:5], 0, v[180:181]
	global_load_lds_dwordx4 v[188:189], off
	s_mov_b32 m0, s14
	v_readfirstlane_b32 s14, v182
	global_load_lds_dwordx4 v[180:181], off
	s_mov_b32 m0, s14
	s_nop 0
	global_load_lds_dwordx4 v[186:187], off
